# gate/up: first K-iteration's two A-half staging loads issued at the head of the previous epilogue (ahead of its stores), third wait no longer depends on store retirement
# speedup vs baseline: 1.0011x; 1.0011x over previous
.LBB0_893:
	s_add_u32 s20, s4, 0xfffc0080
	s_addc_u32 s21, s5, -1
	s_add_i32 s41, 0, 0x10000
	s_cmp_eq_u32 s40, 12
	s_cselect_b32 s23, s15, s21
	s_cselect_b32 s22, s36, s20
	s_cselect_b32 s21, s11, s39
	s_cselect_b32 s20, s37, s38
	s_add_i32 s44, 0, 0x14000
	v_add_u32_e32 v156, s41, v171
	v_add_u32_e32 v164, s44, v171
	ds_read_b128 v[134:137], v156
	ds_read_b128 v[148:151], v156 offset:1024
	ds_read_b128 v[152:155], v156 offset:2048
	ds_read_b128 v[156:159], v156 offset:3072
	ds_read_b128 v[160:163], v164
	ds_read_b128 v[182:185], v164 offset:1024
	ds_read_b128 v[186:189], v164 offset:2048
	ds_read_b128 v[190:193], v164 offset:3072
	s_cmp_eq_i32 s40, -2
	s_cselect_b32 s98, s2, 0
	ds_read_b128 v[194:197], v175
	ds_read_b128 v[198:201], v175 offset:1024
	ds_read_b128 v[202:205], v175 offset:2048
	ds_read_b128 v[206:209], v175 offset:3072
	ds_read_b128 v[210:213], v175 offset:4096
	ds_read_b128 v[214:217], v175 offset:5120
	ds_read_b128 v[218:221], v175 offset:6144
	ds_read_b128 v[222:225], v175 offset:7168
	s_cmp_lg_u32 s98, 0
	s_cbranch_scc1 .Lh3_skip1
	v_lshl_add_u64 v[226:227], s[4:5], 0, v[144:145]
	s_add_i32 m0, s26, 0xc000
	s_nop 0
	global_load_lds_dwordx4 v[226:227], off
	v_lshl_add_u64 v[226:227], s[4:5], 0, v[146:147]
	s_add_i32 m0, s26, 0xe000
	s_nop 0
	global_load_lds_dwordx4 v[226:227], off
.Lh3_skip1:
	s_cmp_lg_u32 s98, 0
	s_cbranch_scc1 .Lh3_relax_w1
	s_waitcnt vmcnt(8)
	s_branch .Lh3_join_w1

.Lh3_join_w1:
	s_waitcnt lgkmcnt(0)
	s_barrier
	s_setprio 1
	s_waitcnt lgkmcnt(0)
	v_mfma_f32_16x16x32_bf16 v[130:133], v[134:137], v[194:197], v[130:133]
	v_mfma_f32_16x16x32_bf16 v[130:133], v[148:151], v[198:201], v[130:133]
	v_mfma_f32_16x16x32_bf16 v[122:125], v[152:155], v[194:197], v[122:125]
	v_mfma_f32_16x16x32_bf16 v[122:125], v[156:159], v[198:201], v[122:125]
	v_mfma_f32_16x16x32_bf16 v[114:117], v[134:137], v[202:205], v[114:117]
	v_mfma_f32_16x16x32_bf16 v[114:117], v[148:151], v[206:209], v[114:117]
	v_mfma_f32_16x16x32_bf16 v[106:109], v[152:155], v[202:205], v[106:109]
	v_mfma_f32_16x16x32_bf16 v[106:109], v[156:159], v[206:209], v[106:109]
	v_mfma_f32_16x16x32_bf16 v[98:101], v[134:137], v[210:213], v[98:101]
	v_mfma_f32_16x16x32_bf16 v[98:101], v[148:151], v[214:217], v[98:101]
	v_mfma_f32_16x16x32_bf16 v[90:93], v[152:155], v[210:213], v[90:93]
	v_mfma_f32_16x16x32_bf16 v[90:93], v[156:159], v[214:217], v[90:93]
	v_mfma_f32_16x16x32_bf16 v[82:85], v[134:137], v[218:221], v[82:85]
	v_mfma_f32_16x16x32_bf16 v[82:85], v[148:151], v[222:225], v[82:85]
	v_mfma_f32_16x16x32_bf16 v[74:77], v[152:155], v[218:221], v[74:77]
	v_mfma_f32_16x16x32_bf16 v[74:77], v[156:159], v[222:225], v[74:77]
	s_setprio 0
	s_setprio 1
	v_mfma_f32_16x16x32_bf16 v[126:129], v[160:163], v[194:197], v[126:129]
	v_mfma_f32_16x16x32_bf16 v[126:129], v[182:185], v[198:201], v[126:129]
	v_mfma_f32_16x16x32_bf16 v[118:121], v[186:189], v[194:197], v[118:121]
	v_mfma_f32_16x16x32_bf16 v[118:121], v[190:193], v[198:201], v[118:121]
	v_mfma_f32_16x16x32_bf16 v[110:113], v[160:163], v[202:205], v[110:113]
	v_mfma_f32_16x16x32_bf16 v[110:113], v[182:185], v[206:209], v[110:113]
	v_mfma_f32_16x16x32_bf16 v[102:105], v[186:189], v[202:205], v[102:105]
	v_mfma_f32_16x16x32_bf16 v[102:105], v[190:193], v[206:209], v[102:105]
	v_mfma_f32_16x16x32_bf16 v[94:97], v[160:163], v[210:213], v[94:97]
	v_mfma_f32_16x16x32_bf16 v[94:97], v[182:185], v[214:217], v[94:97]
	v_mfma_f32_16x16x32_bf16 v[86:89], v[186:189], v[210:213], v[86:89]
	v_mfma_f32_16x16x32_bf16 v[86:89], v[190:193], v[214:217], v[86:89]
	v_mfma_f32_16x16x32_bf16 v[78:81], v[160:163], v[218:221], v[78:81]
	v_mfma_f32_16x16x32_bf16 v[78:81], v[182:185], v[222:225], v[78:81]
	v_mfma_f32_16x16x32_bf16 v[70:73], v[186:189], v[218:221], v[70:73]
	v_mfma_f32_16x16x32_bf16 v[70:73], v[190:193], v[222:225], v[70:73]
	s_setprio 0
	s_barrier
	s_add_i32 s41, s41, s13
	v_lshl_add_u64 v[226:227], s[20:21], 0, v[0:1]
	s_mov_b32 m0, s41
	ds_read_b128 v[194:197], v175 offset:16384
	ds_read_b128 v[198:201], v175 offset:17408
	ds_read_b128 v[202:205], v175 offset:18432
	ds_read_b128 v[206:209], v175 offset:19456
	ds_read_b128 v[210:213], v175 offset:20480
	ds_read_b128 v[214:217], v175 offset:21504
	ds_read_b128 v[218:221], v175 offset:22528
	ds_read_b128 v[222:225], v175 offset:23552
	global_load_lds_dwordx4 v[226:227], off
	s_add_i32 m0, s41, 0x2000
	s_add_u32 s42, s20, 0x40000
	v_lshl_add_u64 v[228:229], s[20:21], 0, v[14:15]
	s_addc_u32 s43, s21, 0
	s_add_i32 s41, s44, s13
	global_load_lds_dwordx4 v[228:229], off
	v_lshl_add_u64 v[230:231], s[42:43], 0, v[0:1]
	s_mov_b32 m0, s41
	v_lshl_add_u64 v[232:233], s[22:23], 0, v[138:139]
	global_load_lds_dwordx4 v[230:231], off
	v_lshl_add_u64 v[230:231], s[42:43], 0, v[14:15]
	s_add_i32 m0, s41, 0x2000
	s_nop 0
	global_load_lds_dwordx4 v[230:231], off
	v_lshl_add_u64 v[230:231], s[22:23], 0, v[140:141]
	s_mov_b32 m0, s26
	s_nop 0
	global_load_lds_dwordx4 v[230:231], off
	s_mov_b32 m0, s27
	s_nop 0
	global_load_lds_dwordx4 v[232:233], off
	s_cmp_lg_u32 s98, 0
	s_cbranch_scc1 .Lh3_relax_w2
	s_waitcnt vmcnt(8)
	s_branch .Lh3_join_w2

.Lh3_join_w2:
	s_waitcnt lgkmcnt(0)
	s_barrier
	s_setprio 1
	s_waitcnt lgkmcnt(0)
	v_mfma_f32_16x16x32_bf16 v[66:69], v[134:137], v[194:197], v[66:69]
	v_mfma_f32_16x16x32_bf16 v[66:69], v[148:151], v[198:201], v[66:69]
	v_mfma_f32_16x16x32_bf16 v[58:61], v[152:155], v[194:197], v[58:61]
	v_mfma_f32_16x16x32_bf16 v[58:61], v[156:159], v[198:201], v[58:61]
	v_mfma_f32_16x16x32_bf16 v[50:53], v[134:137], v[202:205], v[50:53]
	v_mfma_f32_16x16x32_bf16 v[50:53], v[148:151], v[206:209], v[50:53]
	v_mfma_f32_16x16x32_bf16 v[42:45], v[152:155], v[202:205], v[42:45]
	v_mfma_f32_16x16x32_bf16 v[42:45], v[156:159], v[206:209], v[42:45]
	v_mfma_f32_16x16x32_bf16 v[34:37], v[134:137], v[210:213], v[34:37]
	v_mfma_f32_16x16x32_bf16 v[34:37], v[148:151], v[214:217], v[34:37]
	v_mfma_f32_16x16x32_bf16 v[26:29], v[152:155], v[210:213], v[26:29]
	v_mfma_f32_16x16x32_bf16 v[26:29], v[156:159], v[214:217], v[26:29]
	v_mfma_f32_16x16x32_bf16 v[18:21], v[134:137], v[218:221], v[18:21]
	v_mfma_f32_16x16x32_bf16 v[18:21], v[148:151], v[222:225], v[18:21]
	v_mfma_f32_16x16x32_bf16 v[6:9], v[152:155], v[218:221], v[6:9]
	v_mfma_f32_16x16x32_bf16 v[6:9], v[156:159], v[222:225], v[6:9]
	s_setprio 0
	s_setprio 1
	v_mfma_f32_16x16x32_bf16 v[62:65], v[160:163], v[194:197], v[62:65]
	v_mfma_f32_16x16x32_bf16 v[62:65], v[182:185], v[198:201], v[62:65]
	v_mfma_f32_16x16x32_bf16 v[54:57], v[186:189], v[194:197], v[54:57]
	v_mfma_f32_16x16x32_bf16 v[54:57], v[190:193], v[198:201], v[54:57]
	v_mfma_f32_16x16x32_bf16 v[46:49], v[160:163], v[202:205], v[46:49]
	v_mfma_f32_16x16x32_bf16 v[46:49], v[182:185], v[206:209], v[46:49]
	v_mfma_f32_16x16x32_bf16 v[38:41], v[186:189], v[202:205], v[38:41]
	v_mfma_f32_16x16x32_bf16 v[38:41], v[190:193], v[206:209], v[38:41]
	v_mfma_f32_16x16x32_bf16 v[30:33], v[160:163], v[210:213], v[30:33]
	v_mfma_f32_16x16x32_bf16 v[30:33], v[182:185], v[214:217], v[30:33]
	v_mfma_f32_16x16x32_bf16 v[22:25], v[186:189], v[210:213], v[22:25]
	v_mfma_f32_16x16x32_bf16 v[22:25], v[190:193], v[214:217], v[22:25]
	v_mfma_f32_16x16x32_bf16 v[10:13], v[160:163], v[218:221], v[10:13]
	v_mfma_f32_16x16x32_bf16 v[10:13], v[182:185], v[222:225], v[10:13]
	v_mfma_f32_16x16x32_bf16 v[2:5], v[186:189], v[218:221], v[2:5]
	v_mfma_f32_16x16x32_bf16 v[2:5], v[190:193], v[222:225], v[2:5]
	s_setprio 0
	s_barrier
	s_add_i32 s41, 0, 0x18000
	s_add_i32 s42, 0, 0x1c000
	v_add_u32_e32 v156, s41, v171
	v_add_u32_e32 v164, s42, v171
	ds_read_b128 v[134:137], v156
	ds_read_b128 v[148:151], v156 offset:1024
	ds_read_b128 v[152:155], v156 offset:2048
	ds_read_b128 v[156:159], v156 offset:3072
	ds_read_b128 v[160:163], v164
	ds_read_b128 v[182:185], v164 offset:1024
	ds_read_b128 v[186:189], v164 offset:2048
	ds_read_b128 v[190:193], v164 offset:3072
	s_add_u32 s22, s22, 0x40000
	s_addc_u32 s23, s23, 0
	s_mov_b32 m0, s28
	v_lshl_add_u64 v[234:235], s[22:23], 0, v[140:141]
	ds_read_b128 v[194:197], v175 offset:32768
	ds_read_b128 v[198:201], v175 offset:33792
	ds_read_b128 v[202:205], v175 offset:34816
	ds_read_b128 v[206:209], v175 offset:35840
	ds_read_b128 v[210:213], v175 offset:36864
	ds_read_b128 v[214:217], v175 offset:37888
	ds_read_b128 v[218:221], v175 offset:38912
	ds_read_b128 v[222:225], v175 offset:39936
	global_load_lds_dwordx4 v[234:235], off
	v_lshl_add_u64 v[234:235], s[22:23], 0, v[138:139]
	s_mov_b32 m0, s29
	s_nop 0
	global_load_lds_dwordx4 v[234:235], off
	s_cmp_lg_u32 s98, 0
	s_cbranch_scc1 .Lh3_relax_w3
	s_waitcnt vmcnt(8)
	s_branch .Lh3_join_w3

.Lh3_join_w3:
	s_waitcnt lgkmcnt(0)
	s_barrier
	s_setprio 1
	s_waitcnt lgkmcnt(0)
	v_mfma_f32_16x16x32_bf16 v[130:133], v[134:137], v[194:197], v[130:133]
	v_mfma_f32_16x16x32_bf16 v[130:133], v[148:151], v[198:201], v[130:133]
	v_mfma_f32_16x16x32_bf16 v[122:125], v[152:155], v[194:197], v[122:125]
	v_mfma_f32_16x16x32_bf16 v[122:125], v[156:159], v[198:201], v[122:125]
	v_mfma_f32_16x16x32_bf16 v[114:117], v[134:137], v[202:205], v[114:117]
	v_mfma_f32_16x16x32_bf16 v[114:117], v[148:151], v[206:209], v[114:117]
	v_mfma_f32_16x16x32_bf16 v[106:109], v[152:155], v[202:205], v[106:109]
	v_mfma_f32_16x16x32_bf16 v[106:109], v[156:159], v[206:209], v[106:109]
	v_mfma_f32_16x16x32_bf16 v[98:101], v[134:137], v[210:213], v[98:101]
	v_mfma_f32_16x16x32_bf16 v[98:101], v[148:151], v[214:217], v[98:101]
	v_mfma_f32_16x16x32_bf16 v[90:93], v[152:155], v[210:213], v[90:93]
	v_mfma_f32_16x16x32_bf16 v[90:93], v[156:159], v[214:217], v[90:93]
	v_mfma_f32_16x16x32_bf16 v[82:85], v[134:137], v[218:221], v[82:85]
	v_mfma_f32_16x16x32_bf16 v[82:85], v[148:151], v[222:225], v[82:85]
	v_mfma_f32_16x16x32_bf16 v[74:77], v[152:155], v[218:221], v[74:77]
	v_mfma_f32_16x16x32_bf16 v[74:77], v[156:159], v[222:225], v[74:77]
	s_setprio 0
	s_setprio 1
	v_mfma_f32_16x16x32_bf16 v[126:129], v[160:163], v[194:197], v[126:129]
	v_mfma_f32_16x16x32_bf16 v[126:129], v[182:185], v[198:201], v[126:129]
	v_mfma_f32_16x16x32_bf16 v[118:121], v[186:189], v[194:197], v[118:121]
	v_mfma_f32_16x16x32_bf16 v[118:121], v[190:193], v[198:201], v[118:121]
	v_mfma_f32_16x16x32_bf16 v[110:113], v[160:163], v[202:205], v[110:113]
	v_mfma_f32_16x16x32_bf16 v[110:113], v[182:185], v[206:209], v[110:113]
	v_mfma_f32_16x16x32_bf16 v[102:105], v[186:189], v[202:205], v[102:105]
	v_mfma_f32_16x16x32_bf16 v[102:105], v[190:193], v[206:209], v[102:105]
	v_mfma_f32_16x16x32_bf16 v[94:97], v[160:163], v[210:213], v[94:97]
	v_mfma_f32_16x16x32_bf16 v[94:97], v[182:185], v[214:217], v[94:97]
	v_mfma_f32_16x16x32_bf16 v[86:89], v[186:189], v[210:213], v[86:89]
	v_mfma_f32_16x16x32_bf16 v[86:89], v[190:193], v[214:217], v[86:89]
	v_mfma_f32_16x16x32_bf16 v[78:81], v[160:163], v[218:221], v[78:81]
	v_mfma_f32_16x16x32_bf16 v[78:81], v[182:185], v[222:225], v[78:81]
	v_mfma_f32_16x16x32_bf16 v[70:73], v[186:189], v[218:221], v[70:73]
	v_mfma_f32_16x16x32_bf16 v[70:73], v[190:193], v[222:225], v[70:73]
	s_setprio 0
	s_barrier
	s_add_i32 s22, s41, s13
	v_lshl_add_u64 v[226:227], v[226:227], 0, s[92:93]
	s_mov_b32 m0, s22
	ds_read_b128 v[194:197], v175 offset:49152
	ds_read_b128 v[198:201], v175 offset:50176
	ds_read_b128 v[202:205], v175 offset:51200
	ds_read_b128 v[206:209], v175 offset:52224
	ds_read_b128 v[210:213], v175 offset:53248
	ds_read_b128 v[214:217], v175 offset:54272
	ds_read_b128 v[218:221], v175 offset:55296
	ds_read_b128 v[222:225], v175 offset:56320
	global_load_lds_dwordx4 v[226:227], off
	s_add_i32 m0, s22, 0x2000
	s_add_u32 s20, s20, 0x40080
	v_lshl_add_u64 v[226:227], v[228:229], 0, s[92:93]
	s_addc_u32 s21, s21, 0
	s_add_i32 s22, s42, s13
	global_load_lds_dwordx4 v[226:227], off
	v_lshl_add_u64 v[226:227], s[20:21], 0, v[0:1]
	s_mov_b32 m0, s22
	s_nop 0
	global_load_lds_dwordx4 v[226:227], off
	v_lshl_add_u64 v[226:227], s[20:21], 0, v[14:15]
	s_add_i32 m0, s22, 0x2000
	s_nop 0
	global_load_lds_dwordx4 v[226:227], off
	v_lshl_add_u64 v[226:227], v[230:231], 0, s[92:93]
	s_mov_b32 m0, s30
	s_nop 0
	global_load_lds_dwordx4 v[226:227], off
	v_lshl_add_u64 v[226:227], v[232:233], 0, s[92:93]
	s_mov_b32 m0, s31
	s_nop 0
	global_load_lds_dwordx4 v[226:227], off
	s_waitcnt vmcnt(8)
	s_waitcnt lgkmcnt(0)
	s_barrier
	s_setprio 1
	s_waitcnt lgkmcnt(0)
	v_mfma_f32_16x16x32_bf16 v[66:69], v[134:137], v[194:197], v[66:69]
	v_mfma_f32_16x16x32_bf16 v[66:69], v[148:151], v[198:201], v[66:69]
	v_mfma_f32_16x16x32_bf16 v[58:61], v[152:155], v[194:197], v[58:61]
	v_mfma_f32_16x16x32_bf16 v[58:61], v[156:159], v[198:201], v[58:61]
	v_mfma_f32_16x16x32_bf16 v[50:53], v[134:137], v[202:205], v[50:53]
	v_mfma_f32_16x16x32_bf16 v[50:53], v[148:151], v[206:209], v[50:53]
	v_mfma_f32_16x16x32_bf16 v[42:45], v[152:155], v[202:205], v[42:45]
	v_mfma_f32_16x16x32_bf16 v[42:45], v[156:159], v[206:209], v[42:45]
	v_mfma_f32_16x16x32_bf16 v[34:37], v[134:137], v[210:213], v[34:37]
	v_mfma_f32_16x16x32_bf16 v[34:37], v[148:151], v[214:217], v[34:37]
	v_mfma_f32_16x16x32_bf16 v[26:29], v[152:155], v[210:213], v[26:29]
	v_mfma_f32_16x16x32_bf16 v[26:29], v[156:159], v[214:217], v[26:29]
	v_mfma_f32_16x16x32_bf16 v[18:21], v[134:137], v[218:221], v[18:21]
	v_mfma_f32_16x16x32_bf16 v[18:21], v[148:151], v[222:225], v[18:21]
	v_mfma_f32_16x16x32_bf16 v[6:9], v[152:155], v[218:221], v[6:9]
	v_mfma_f32_16x16x32_bf16 v[6:9], v[156:159], v[222:225], v[6:9]
	s_setprio 0
	s_setprio 1
	v_mfma_f32_16x16x32_bf16 v[62:65], v[160:163], v[194:197], v[62:65]
	v_mfma_f32_16x16x32_bf16 v[62:65], v[182:185], v[198:201], v[62:65]
	v_mfma_f32_16x16x32_bf16 v[54:57], v[186:189], v[194:197], v[54:57]
	v_mfma_f32_16x16x32_bf16 v[54:57], v[190:193], v[198:201], v[54:57]
	v_mfma_f32_16x16x32_bf16 v[46:49], v[160:163], v[202:205], v[46:49]
	v_mfma_f32_16x16x32_bf16 v[46:49], v[182:185], v[206:209], v[46:49]
	v_mfma_f32_16x16x32_bf16 v[38:41], v[186:189], v[202:205], v[38:41]
	v_mfma_f32_16x16x32_bf16 v[38:41], v[190:193], v[206:209], v[38:41]
	v_mfma_f32_16x16x32_bf16 v[30:33], v[160:163], v[210:213], v[30:33]
	v_mfma_f32_16x16x32_bf16 v[30:33], v[182:185], v[214:217], v[30:33]
	v_mfma_f32_16x16x32_bf16 v[22:25], v[186:189], v[210:213], v[22:25]
	v_mfma_f32_16x16x32_bf16 v[22:25], v[190:193], v[214:217], v[22:25]
	v_mfma_f32_16x16x32_bf16 v[10:13], v[160:163], v[218:221], v[10:13]
	v_mfma_f32_16x16x32_bf16 v[10:13], v[182:185], v[222:225], v[10:13]
	v_mfma_f32_16x16x32_bf16 v[2:5], v[186:189], v[218:221], v[2:5]
	v_mfma_f32_16x16x32_bf16 v[2:5], v[190:193], v[222:225], v[2:5]
	s_setprio 0
	s_barrier
	s_add_i32 s40, s40, 2
	s_add_u32 s4, s4, 0x100
	s_addc_u32 s5, s5, 0
	s_add_u32 s38, s38, 0x100
	s_addc_u32 s39, s39, 0
	s_cmp_gt_u32 s40, 13
	s_cbranch_scc0 .LBB0_893
	s_and_b64 vcc, exec, s[8:9]
	s_cbranch_vccz .LBB0_896
	s_barrier
.LBB0_896:
	s_mov_b64 s[100:101], 0x40080
	v_lshl_add_u64 v[226:227], s[16:17], 0, v[144:145]
	v_lshl_add_u64 v[226:227], v[226:227], 0, s[100:101]
	s_add_i32 m0, s26, 0xc000
	v_lshl_add_u64 v[228:229], s[16:17], 0, v[146:147]
	global_load_lds_dwordx4 v[226:227], off
	v_lshl_add_u64 v[228:229], v[228:229], 0, s[100:101]
	s_add_i32 m0, s26, 0xe000
	s_nop 0
	global_load_lds_dwordx4 v[228:229], off
	v_lshl_add_u32 v162, s3, 8, v167
	v_or_b32_e32 v160, 16, v162
	v_or_b32_e32 v158, 32, v162
	v_or_b32_e32 v156, 48, v162
	v_add_u32_e32 v154, 0x80, v162
	v_add_u32_e32 v152, 0x90, v162
	v_add_u32_e32 v150, 0xa0, v162
	v_add_u32_e32 v148, 0xb0, v162
	s_mov_b64 s[4:5], -1
	s_cmp_gt_u32 s2, 11
	v_ashrrev_i32_e32 v163, 31, v162
	v_ashrrev_i32_e32 v161, 31, v160
	v_ashrrev_i32_e32 v159, 31, v158
	v_ashrrev_i32_e32 v157, 31, v156
	v_ashrrev_i32_e32 v155, 31, v154
	v_ashrrev_i32_e32 v153, 31, v152
	v_ashrrev_i32_e32 v151, 31, v150
	v_ashrrev_i32_e32 v149, 31, v148
	s_cbranch_scc1 .LBB0_898
	s_lshl_b32 s2, s2, 10
	s_add_i32 s2, s2, 0
	v_add_u32_e32 v134, s2, v169
	v_add_u32_e32 v135, 0x20ac0, v134
	v_add_u32_e32 v164, 0x20a00, v134
	v_add_u32_e32 v168, 0x208c0, v134
	v_add_u32_e32 v170, 0x20880, v134
	v_add_u32_e32 v172, 0x20840, v134
	v_add_u32_e32 v136, 0x20a80, v134
	v_add_u32_e32 v137, 0x20a40, v134
	v_add_u32_e32 v183, 0x20800, v134
	ds_read_b32 v134, v135
	ds_read_b32 v182, v136
	ds_read_b32 v174, v137
	ds_read_b32 v166, v164
	ds_read_b32 v164, v168
	ds_read_b32 v168, v170
	ds_read_b32 v170, v172
	ds_read_b32 v172, v183
	s_mov_b64 s[4:5], 0
